# fox inner loop: S1 MFMAs early, overlapped bpermutes, V frags preloaded into freed regs, PV MFMAs interleaved with exp VALU
# speedup vs baseline: 1.1579x; 1.0101x over previous
; #define MFMA(a, b, c) __builtin_amdgcn_mfma_f32_32x32x16_f16(__builtin_bit_cast(h16x8, (a)), __builtin_bit_cast(h16x8, (b)), (c), 0, 0, 0)
; DI unsigned pk2(float a, float b) { f2_t v = {a, b}; bf2_t r = __builtin_convertvector(v, bf2_t); return __builtin_bit_cast(unsigned, r); }
; template <int MODE> ...
;     ...
;             const float mc = m[nb];
;             float ps = 0.f;
; #pragma unroll
;             for (int i = 0; i < 16; ++i) {
;               sv[i] = __builtin_amdgcn_exp2f(sv[i] - mc);
;               ps += sv[i];
;             }
;             l[nb] += ps;
; #pragma unroll
;             for (int s2 = 0; s2 < 2; ++s2) {
;               const unsigned u0 = pk2(sv[8 * s2], sv[8 * s2 + 1]), u1 = pk2(sv[8 * s2 + 2], sv[8 * s2 + 3]);
;               const unsigned u2 = pk2(sv[8 * s2 + 4], sv[8 * s2 + 5]), u3 = pk2(sv[8 * s2 + 6], sv[8 * s2 + 7]);
;               const uint4 uu = make_uint4(u0, u1, u2, u3);
;               pk[nb][s2] = __builtin_bit_cast(bf16x8, uu);
;             }
;           }
;         }
;         if (MODE != M_CMP2) {
; #pragma unroll
;           for (int s2 = 0; s2 < 2; ++s2) {
; #pragma unroll
;             for (int db = 0; db < 2; ++db) {
;               const u16* vp = Vt + (kb * 32 + 16 * s2 + 4 * h + q4) * LDK + db * 32 + 16 * blk + 4 * p4;
;               const s16x4 lo = __builtin_amdgcn_ds_read_tr16_b64_v4i16((__attribute__((address_space(3))) s16x4*)(vp));
;               const s16x4 hi = __builtin_amdgcn_ds_read_tr16_b64_v4i16((__attribute__((address_space(3))) s16x4*)(vp + 8 * LDK));
;               const bf16x8 a = __builtin_shufflevector(lo, hi, 0, 1, 2, 3, 4, 5, 6, 7);
;               O[db][0] = MFMA(a, pk[0][s2], O[db][0]);
;               O[db][1] = MFMA(a, pk[1][s2], O[db][1]);
;             }
;           }
.LBB0_647:
	v_or_b32_e32 v83, s22, v245
	v_mad_u32_u24 v83, v83, s76, v222
	ds_read_b64_tr_b16 v[84:85], v83 offset:18432
	ds_read_b64_tr_b16 v[86:87], v83 offset:19584
	ds_read_b64_tr_b16 v[88:89], v83 offset:18496
	ds_read_b64_tr_b16 v[90:91], v83 offset:19648
	ds_read_b64_tr_b16 v[92:93], v83 offset:20736
	ds_read_b64_tr_b16 v[94:95], v83 offset:21888
	ds_read_b64_tr_b16 v[96:97], v83 offset:20800
	ds_read_b64_tr_b16 v[98:99], v83 offset:21952
	v_sub_f32_e32 v112, v112, v219
	v_exp_f32_e32 v112, v112
	v_sub_f32_e32 v113, v113, v219
	v_exp_f32_e32 v113, v113
	v_add_f32_e32 v100, 0, v112
	v_sub_f32_e32 v114, v114, v219
	v_exp_f32_e32 v114, v114
	v_add_f32_e32 v100, v113, v100
	v_sub_f32_e32 v115, v115, v219
	v_exp_f32_e32 v115, v115
	v_add_f32_e32 v100, v114, v100
	v_sub_f32_e32 v116, v116, v219
	v_exp_f32_e32 v116, v116
	v_add_f32_e32 v100, v115, v100
	v_sub_f32_e32 v117, v117, v219
	v_exp_f32_e32 v117, v117
	v_add_f32_e32 v100, v116, v100
	v_sub_f32_e32 v118, v118, v219
	v_exp_f32_e32 v118, v118
	v_add_f32_e32 v100, v117, v100
	v_sub_f32_e32 v119, v119, v219
	v_exp_f32_e32 v119, v119
	v_add_f32_e32 v100, v118, v100
	v_sub_f32_e32 v120, v120, v219
	v_exp_f32_e32 v120, v120
	v_add_f32_e32 v100, v119, v100
	v_sub_f32_e32 v121, v121, v219
	v_exp_f32_e32 v121, v121
	v_add_f32_e32 v100, v120, v100
	v_sub_f32_e32 v122, v122, v219
	v_exp_f32_e32 v122, v122
	v_add_f32_e32 v100, v121, v100
	v_sub_f32_e32 v123, v123, v219
	v_exp_f32_e32 v123, v123
	v_add_f32_e32 v100, v122, v100
	v_sub_f32_e32 v124, v124, v219
	v_exp_f32_e32 v124, v124
	v_add_f32_e32 v100, v123, v100
	v_sub_f32_e32 v125, v125, v219
	v_exp_f32_e32 v125, v125
	v_add_f32_e32 v100, v124, v100
	v_sub_f32_e32 v126, v126, v219
	v_exp_f32_e32 v126, v126
	v_add_f32_e32 v100, v125, v100
	v_sub_f32_e32 v127, v127, v219
	v_exp_f32_e32 v127, v127
	v_add_f32_e32 v100, v126, v100
	v_add_f32_e32 v100, v127, v100
	v_cvt_pk_f16_f32 v104, v112, v113
	v_cvt_pk_f16_f32 v105, v114, v115
	v_cvt_pk_f16_f32 v106, v116, v117
	v_cvt_pk_f16_f32 v107, v118, v119
	v_cvt_pk_f16_f32 v108, v120, v121
	v_cvt_pk_f16_f32 v109, v122, v123
	v_cvt_pk_f16_f32 v110, v124, v125
	v_cvt_pk_f16_f32 v111, v126, v127
	v_add_f32_e32 v208, v208, v100
	v_mov_b32_e32 v213, v208
	s_waitcnt lgkmcnt(6)
	v_mfma_f32_32x32x16_f16 v[64:79], v[84:87], v[104:107], v[64:79]
	v_sub_f32_e32 v128, v128, v14
	v_exp_f32_e32 v128, v128
	v_sub_f32_e32 v129, v129, v14
	v_exp_f32_e32 v129, v129
	v_add_f32_e32 v101, 0, v128
	v_sub_f32_e32 v130, v130, v14
	v_exp_f32_e32 v130, v130
	v_add_f32_e32 v101, v129, v101
	v_sub_f32_e32 v131, v131, v14
	s_waitcnt lgkmcnt(4)
	v_mfma_f32_32x32x16_f16 v[48:63], v[88:91], v[104:107], v[48:63]
	v_exp_f32_e32 v131, v131
	v_add_f32_e32 v101, v130, v101
	v_sub_f32_e32 v132, v132, v14
	v_exp_f32_e32 v132, v132
	v_add_f32_e32 v101, v131, v101
	v_sub_f32_e32 v133, v133, v14
	v_exp_f32_e32 v133, v133
	v_add_f32_e32 v101, v132, v101
	v_sub_f32_e32 v134, v134, v14
	s_waitcnt lgkmcnt(2)
	v_mfma_f32_32x32x16_f16 v[64:79], v[92:95], v[108:111], v[64:79]
	v_exp_f32_e32 v134, v134
	v_add_f32_e32 v101, v133, v101
	v_sub_f32_e32 v135, v135, v14
	v_exp_f32_e32 v135, v135
	v_add_f32_e32 v101, v134, v101
	v_cvt_pk_f16_f32 v2, v128, v129
	v_cvt_pk_f16_f32 v3, v130, v131
	v_cvt_pk_f16_f32 v4, v132, v133
	v_cvt_pk_f16_f32 v5, v134, v135
	s_waitcnt lgkmcnt(0)
	v_mfma_f32_32x32x16_f16 v[48:63], v[96:99], v[108:111], v[48:63]
	s_nop 1
	v_mfma_f32_32x32x16_f16 v[32:47], v[84:87], v[2:5], v[32:47]
	v_sub_f32_e32 v136, v136, v14
	v_exp_f32_e32 v136, v136
	v_add_f32_e32 v101, v135, v101
	v_sub_f32_e32 v137, v137, v14
	v_exp_f32_e32 v137, v137
	v_add_f32_e32 v101, v136, v101
	v_sub_f32_e32 v138, v138, v14
	v_exp_f32_e32 v138, v138
	v_add_f32_e32 v101, v137, v101
	v_mfma_f32_32x32x16_f16 v[16:31], v[88:91], v[2:5], v[16:31]
	v_sub_f32_e32 v139, v139, v14
	v_exp_f32_e32 v139, v139
	v_add_f32_e32 v101, v138, v101
	v_sub_f32_e32 v140, v140, v14
	v_exp_f32_e32 v140, v140
	v_add_f32_e32 v101, v139, v101
	v_sub_f32_e32 v141, v141, v14
	v_exp_f32_e32 v141, v141
	v_add_f32_e32 v101, v140, v101
	v_sub_f32_e32 v142, v142, v14
	v_exp_f32_e32 v142, v142
	v_add_f32_e32 v101, v141, v101
	v_sub_f32_e32 v143, v143, v14
	v_exp_f32_e32 v143, v143
	v_add_f32_e32 v101, v142, v101
	v_add_f32_e32 v101, v143, v101
	v_cvt_pk_f16_f32 v6, v136, v137
	v_cvt_pk_f16_f32 v7, v138, v139
	v_cvt_pk_f16_f32 v8, v140, v141
	v_cvt_pk_f16_f32 v9, v142, v143
	v_add_f32_e32 v212, v212, v101
	s_nop 1
	v_mfma_f32_32x32x16_f16 v[32:47], v[92:95], v[6:9], v[32:47]
	v_mfma_f32_32x32x16_f16 v[16:31], v[96:99], v[6:9], v[16:31]

; #define MFMA(a, b, c) __builtin_amdgcn_mfma_f32_32x32x16_f16(__builtin_bit_cast(h16x8, (a)), __builtin_bit_cast(h16x8, (b)), (c), 0, 0, 0)
; template <int MODE> ...
;     ...
;       bool need = true;
;       if (MODE == M_FOX || MODE == M_SLC) need = (kbase <= wq0 + 63);
;       if (MODE == M_WIN) need = (kbase <= wq0 + 63) && (kbase + 31 > wq0 - 512);
;       if (MODE == M_CMP) need = (16 * kbase + 31 <= wq0 + 63);
;       float mainv[2][4], spill[2][4];
;       if (need) {
;         bool domask = true;
;         if (MODE == M_FOX || MODE == M_SLC) domask = (kbase + 31 > wq0);
;         if (MODE == M_WIN) domask = (kbase + 31 > wq0) || (kbase <= wq0 + 63 - 512);
;         bf16x8 pk[2][2];
; #pragma unroll
;         for (int nb = 0; nb < 2; ++nb) {
;           f32x16 Sn;
;           if (MODE == M_FOX) {
; #pragma unroll
;             for (int a4 = 0; a4 < 4; ++a4) {
;               const float4 c4 = *(const float4*)(ckt + kb * 32 + 8 * a4 + 4 * h);
;               Sn[4 * a4] = cq[nb] - c4.x; Sn[4 * a4 + 1] = cq[nb] - c4.y; Sn[4 * a4 + 2] = cq[nb] - c4.z; Sn[4 * a4 + 3] = cq[nb] - c4.w;
;             }
;           } else {
; #pragma unroll
;             for (int i = 0; i < 16; ++i) Sn[i] = 0.f;
;           }
; #pragma unroll
;           for (int ks = 0; ks < 4; ++ks) {
;             const bf16x8 a = *(const bf16x8*)(Kt + (kb * 32 + r) * LDK + ks * 16 + 8 * h);
;             Sn = MFMA(a, qf[nb][ks], Sn);
;           }
;           float sv[16];
;           const int t = qpos[nb];
;           bool sb = true;
;           if (MODE == M_SLC) sb = (((selb[nb] >> (key0 >> 6)) & 1ull) != 0ull);
;           if (domask) {
; #pragma unroll
;             for (int i = 0; i < 16; ++i) {
;               const int kk = kbase + (i & 3) + 8 * (i >> 2) + 4 * h;
;               bool valid;
;               if (MODE == M_FOX) valid = (kk <= t);
;               else if (MODE == M_CMP || MODE == M_CMP2) valid = (16 * kk + 31 <= t) && (kk < 255);
;               else if (MODE == M_SLC) valid = sb && (kk <= t);
;               else valid = (kk <= t) && (kk > t - 512);
;               sv[i] = valid ? Sn[i] : -INFINITY;
.LBB0_649:
	s_or_b32 s14, s22, s21
	v_cmp_le_i32_e32 vcc, s14, v241
	s_and_saveexec_b64 s[12:13], vcc
	s_cbranch_execz .LBB0_648
	v_or_b32_e32 v2, s22, v240
	v_lshl_add_u32 v112, s22, 2, v0
	v_mad_u32_u24 v132, v2, s76, v15
	ds_read_b128 v[2:5], v112 offset:36960
	ds_read_b128 v[6:9], v112 offset:36928
	ds_read_b128 v[10:13], v112 offset:36896
	ds_read_b128 v[128:131], v112 offset:36864
	ds_read_b128 v[196:199], v132
	ds_read_b128 v[192:195], v132 offset:32
	s_waitcnt lgkmcnt(5)
	v_sub_f32_e32 v127, v80, v5
	v_sub_f32_e32 v126, v80, v4
	v_sub_f32_e32 v125, v80, v3
	v_sub_f32_e32 v124, v80, v2
	s_waitcnt lgkmcnt(4)
	v_sub_f32_e32 v123, v80, v9
	v_sub_f32_e32 v122, v80, v8
	v_sub_f32_e32 v121, v80, v7
	v_sub_f32_e32 v120, v80, v6
	s_waitcnt lgkmcnt(3)
	v_sub_f32_e32 v119, v80, v13
	v_sub_f32_e32 v118, v80, v12
	v_sub_f32_e32 v117, v80, v11
	v_sub_f32_e32 v116, v80, v10
	s_waitcnt lgkmcnt(2)
	v_sub_f32_e32 v115, v80, v131
	v_sub_f32_e32 v114, v80, v130
	v_sub_f32_e32 v113, v80, v129
	v_sub_f32_e32 v112, v80, v128
	ds_read_b128 v[204:207], v132 offset:64
	ds_read_b128 v[200:203], v132 offset:96
	s_waitcnt lgkmcnt(3)
	v_mfma_f32_32x32x16_f16 v[112:127], v[196:199], v[144:147], v[112:127]
	s_or_b32 s0, s14, 31
	v_cmp_gt_i32_e64 s[0:1], s0, v232
	v_or_b32_e32 v213, s14, v244
	v_sub_f32_e32 v143, v82, v5
	v_sub_f32_e32 v142, v82, v4
	v_sub_f32_e32 v141, v82, v3
	v_sub_f32_e32 v140, v82, v2
	s_waitcnt lgkmcnt(2)
	v_mfma_f32_32x32x16_f16 v[112:127], v[192:195], v[148:151], v[112:127]
	v_sub_f32_e32 v139, v82, v9
	v_sub_f32_e32 v138, v82, v8
	v_sub_f32_e32 v137, v82, v7
	v_sub_f32_e32 v136, v82, v6
	s_waitcnt lgkmcnt(1)
	v_mfma_f32_32x32x16_f16 v[112:127], v[204:207], v[152:155], v[112:127]
	v_sub_f32_e32 v135, v82, v13
	v_sub_f32_e32 v134, v82, v12
	v_sub_f32_e32 v133, v82, v11
	v_sub_f32_e32 v132, v82, v10
	s_waitcnt lgkmcnt(0)
	v_mfma_f32_32x32x16_f16 v[112:127], v[200:203], v[156:159], v[112:127]
	v_sub_f32_e32 v131, v82, v131
	v_sub_f32_e32 v130, v82, v130
	v_sub_f32_e32 v129, v82, v129
	v_sub_f32_e32 v128, v82, v128
	s_nop 1
	v_mfma_f32_32x32x16_f16 v[128:143], v[196:199], v[160:163], v[128:143]
	v_mfma_f32_32x32x16_f16 v[128:143], v[192:195], v[164:167], v[128:143]
	v_mfma_f32_32x32x16_f16 v[128:143], v[204:207], v[168:171], v[128:143]
	v_mfma_f32_32x32x16_f16 v[128:143], v[200:203], v[172:175], v[128:143]
	s_and_saveexec_b64 s[14:15], s[0:1]
	s_cbranch_execz .LBB0_652
	v_cmp_le_i32_e32 vcc, v213, v214
	v_or_b32_e32 v2, 2, v213
	s_nop 7
	v_cndmask_b32_e32 v112, v227, v112, vcc
	v_cmp_lt_i32_e32 vcc, v213, v214
	s_nop 1
	v_cndmask_b32_e32 v113, v227, v113, vcc
	v_cmp_le_i32_e32 vcc, v2, v214
	v_or_b32_e32 v2, 3, v213
	s_nop 0
	v_cndmask_b32_e32 v114, v227, v114, vcc
	v_cmp_le_i32_e32 vcc, v2, v214
	v_or_b32_e32 v2, 8, v213
	s_nop 0
	v_cndmask_b32_e32 v115, v227, v115, vcc
	v_cmp_le_i32_e32 vcc, v2, v214
	v_or_b32_e32 v2, 9, v213
	s_nop 0
	v_cndmask_b32_e32 v116, v227, v116, vcc
	v_cmp_le_i32_e32 vcc, v2, v214
	v_or_b32_e32 v2, 10, v213
	s_nop 0
	v_cndmask_b32_e32 v117, v227, v117, vcc
	v_cmp_le_i32_e32 vcc, v2, v214
	v_or_b32_e32 v2, 11, v213
	s_nop 0
	v_cndmask_b32_e32 v118, v227, v118, vcc
	v_cmp_le_i32_e32 vcc, v2, v214
	v_or_b32_e32 v2, 16, v213
	s_nop 0
	v_cndmask_b32_e32 v119, v227, v119, vcc
	v_cmp_le_i32_e32 vcc, v2, v214
	v_or_b32_e32 v2, 17, v213
	s_nop 0
	v_cndmask_b32_e32 v120, v227, v120, vcc
	v_cmp_le_i32_e32 vcc, v2, v214
	v_or_b32_e32 v2, 18, v213
	s_nop 0
	v_cndmask_b32_e32 v121, v227, v121, vcc
	v_cmp_le_i32_e32 vcc, v2, v214
	v_or_b32_e32 v2, 19, v213
	s_nop 0
	v_cndmask_b32_e32 v122, v227, v122, vcc
	v_cmp_le_i32_e32 vcc, v2, v214
	v_or_b32_e32 v2, 24, v213
	s_nop 0
	v_cndmask_b32_e32 v123, v227, v123, vcc
	v_cmp_le_i32_e32 vcc, v2, v214
	v_or_b32_e32 v2, 25, v213
	s_nop 0
	v_cndmask_b32_e32 v124, v227, v124, vcc
	v_cmp_le_i32_e32 vcc, v2, v214
	v_or_b32_e32 v2, 26, v213
	s_nop 0
	v_cndmask_b32_e32 v125, v227, v125, vcc
	v_cmp_le_i32_e32 vcc, v2, v214
	v_or_b32_e32 v2, 27, v213
	s_nop 0
	v_cndmask_b32_e32 v126, v227, v126, vcc
	v_cmp_le_i32_e32 vcc, v2, v214
	s_nop 1
	v_cndmask_b32_e32 v127, v227, v127, vcc
; template <int MODE> ...
;     ...
;           if (domask) {
; #pragma unroll
;             for (int i = 0; i < 16; ++i) {
;               const int kk = kbase + (i & 3) + 8 * (i >> 2) + 4 * h;
;               bool valid;
;               if (MODE == M_FOX) valid = (kk <= t);
;               else if (MODE == M_CMP || MODE == M_CMP2) valid = (16 * kk + 31 <= t) && (kk < 255);
;               else if (MODE == M_SLC) valid = sb && (kk <= t);
;               else valid = (kk <= t) && (kk > t - 512);
;               sv[i] = valid ? Sn[i] : -INFINITY;
;             }
;           } else {
; #pragma unroll
;             for (int i = 0; i < 16; ++i) sv[i] = (MODE == M_SLC) ? (sb ? Sn[i] : -INFINITY) : Sn[i];
;           }
;           if (MODE == M_CMP2) {
; #pragma unroll
;             for (int a4 = 0; a4 < 4; ++a4) {
;               float pe[4];
; #pragma unroll
;               for (int e = 0; e < 4; ++e) pe[e] = __builtin_amdgcn_exp2f(sv[4 * a4 + e] - m[nb]) * linv[nb];
;               mainv[nb][a4] = pe[0] + pe[1] + pe[2] + 0.5f * pe[3];
;               spill[nb][a4] = 0.5f * pe[3];
;             }
;           } else {
;             float mx = sv[0];
; #pragma unroll
;             for (int i = 1; i < 16; ++i) mx = fmaxf(mx, sv[i]);
;             mx = fmaxf(mx, shx(mx, lane, 32));
;             if (__any(mx > m[nb] + 8.f)) {
;               const float mnew = (mx > m[nb] + 8.f) ? mx : m[nb];
;               const float alpha = __builtin_amdgcn_exp2f(m[nb] - mnew);
;               m[nb] = mnew;
;               l[nb] *= alpha;
; #pragma unroll
;               for (int i = 0; i < 16; ++i) { O[0][nb][i] *= alpha; O[1][nb][i] *= alpha; }
;             }
.LBB0_652:
	s_or_b64 exec, exec, s[14:15]
	s_nop 1
	v_max_f32_e32 v2, v113, v113
	v_max_f32_e32 v3, v112, v112
	v_max_f32_e32 v2, v3, v2
	v_max3_f32 v2, v2, v114, v115
	v_max3_f32 v2, v2, v116, v117
	v_max3_f32 v2, v2, v118, v119
	v_max3_f32 v2, v2, v120, v121
	v_max3_f32 v2, v2, v122, v123
	v_max3_f32 v2, v2, v124, v125
	v_max3_f32 v2, v2, v126, v127
	ds_bpermute_b32 v3, v243, v2
	s_and_saveexec_b64 s[14:15], s[0:1]
	s_cbranch_execz .LBB0_656
	v_cmp_le_i32_e32 vcc, v213, v233
	s_nop 8
	v_cndmask_b32_e32 v128, v227, v128, vcc
	v_cmp_lt_i32_e32 vcc, v213, v233
	s_nop 1
	v_cndmask_b32_e32 v129, v227, v129, vcc
	v_cmp_le_i32_e32 vcc, v213, v247
	s_nop 1
	v_cndmask_b32_e32 v130, v227, v130, vcc
	v_cmp_le_i32_e32 vcc, v213, v248
	s_nop 1
	v_cndmask_b32_e32 v131, v227, v131, vcc
	v_cmp_le_i32_e32 vcc, v213, v249
	s_nop 1
	v_cndmask_b32_e32 v132, v227, v132, vcc
	v_cmp_le_i32_e32 vcc, v213, v250
	s_nop 1
	v_cndmask_b32_e32 v133, v227, v133, vcc
	v_cmp_le_i32_e32 vcc, v213, v218
	s_nop 1
	v_cndmask_b32_e32 v134, v227, v134, vcc
	v_cmp_le_i32_e32 vcc, v213, v216
	s_nop 1
	v_cndmask_b32_e32 v135, v227, v135, vcc
	v_cmp_le_i32_e32 vcc, v213, v217
	s_nop 1
	v_cndmask_b32_e32 v136, v227, v136, vcc
	v_cmp_le_i32_e32 vcc, v213, v228
	s_nop 1
	v_cndmask_b32_e32 v137, v227, v137, vcc
	v_cmp_le_i32_e32 vcc, v213, v229
	s_nop 1
	v_cndmask_b32_e32 v138, v227, v138, vcc
	v_cmp_le_i32_e32 vcc, v213, v230
	s_nop 1
	v_cndmask_b32_e32 v139, v227, v139, vcc
	v_cmp_le_i32_e32 vcc, v213, v231
	s_nop 1
	v_cndmask_b32_e32 v140, v227, v140, vcc
	v_cmp_le_i32_e32 vcc, v213, v223
	s_nop 1
	v_cndmask_b32_e32 v141, v227, v141, vcc
	v_cmp_le_i32_e32 vcc, v213, v226
	s_nop 1
	v_cndmask_b32_e32 v142, v227, v142, vcc
	v_cmp_le_i32_e32 vcc, v213, v221
	s_nop 1
	v_cndmask_b32_e32 v143, v227, v143, vcc
.LBB0_656:
	s_or_b64 exec, exec, s[14:15]
	s_nop 1
	v_max_f32_e32 v4, v129, v129
	v_max_f32_e32 v5, v128, v128
	v_max_f32_e32 v4, v5, v4
	v_max3_f32 v4, v4, v130, v131
	v_max3_f32 v4, v4, v132, v133
	v_max3_f32 v4, v4, v134, v135
	v_max3_f32 v4, v4, v136, v137
	v_max3_f32 v4, v4, v138, v139
	v_max3_f32 v4, v4, v140, v141
	v_max3_f32 v4, v4, v142, v143
	ds_bpermute_b32 v5, v243, v4
	s_waitcnt lgkmcnt(1)
	v_max_f32_e32 v3, v3, v3
	v_max_f32_e32 v2, v2, v3
	v_add_f32_e32 v3, 0x41000000, v219
	v_cmp_gt_f32_e32 vcc, v2, v3
	s_cbranch_vccz .LBB0_654
	s_nop 0
	v_cndmask_b32_e32 v3, v219, v2, vcc
	v_sub_f32_e32 v2, v219, v3
	v_exp_f32_e32 v2, v2
	v_mov_b32_e32 v219, v3
	v_mul_f32_e32 v208, v208, v2
	v_pk_mul_f32 v[78:79], v[78:79], v[2:3] op_sel_hi:[1,0]
	v_pk_mul_f32 v[76:77], v[76:77], v[2:3] op_sel_hi:[1,0]
	v_pk_mul_f32 v[74:75], v[74:75], v[2:3] op_sel_hi:[1,0]
	v_pk_mul_f32 v[72:73], v[72:73], v[2:3] op_sel_hi:[1,0]
	v_pk_mul_f32 v[70:71], v[70:71], v[2:3] op_sel_hi:[1,0]
	v_pk_mul_f32 v[68:69], v[68:69], v[2:3] op_sel_hi:[1,0]
	v_pk_mul_f32 v[66:67], v[66:67], v[2:3] op_sel_hi:[1,0]
	v_pk_mul_f32 v[64:65], v[64:65], v[2:3] op_sel_hi:[1,0]
	v_pk_mul_f32 v[62:63], v[62:63], v[2:3] op_sel_hi:[1,0]
	v_pk_mul_f32 v[60:61], v[60:61], v[2:3] op_sel_hi:[1,0]
	v_pk_mul_f32 v[58:59], v[58:59], v[2:3] op_sel_hi:[1,0]
	v_pk_mul_f32 v[56:57], v[56:57], v[2:3] op_sel_hi:[1,0]
	v_pk_mul_f32 v[54:55], v[54:55], v[2:3] op_sel_hi:[1,0]
	v_pk_mul_f32 v[52:53], v[52:53], v[2:3] op_sel_hi:[1,0]
	v_pk_mul_f32 v[50:51], v[50:51], v[2:3] op_sel_hi:[1,0]
	v_pk_mul_f32 v[48:49], v[48:49], v[2:3] op_sel_hi:[1,0]
.LBB0_654:
	s_waitcnt lgkmcnt(0)
	v_max_f32_e32 v5, v5, v5
	v_max_f32_e32 v4, v4, v5
	v_add_f32_e32 v5, 0x41000000, v14
	v_cmp_gt_f32_e32 vcc, v4, v5
	s_cbranch_vccz .LBB0_647
	s_nop 0
	v_cndmask_b32_e32 v5, v14, v4, vcc
	v_sub_f32_e32 v4, v14, v5
	v_exp_f32_e32 v4, v4
	v_mov_b32_e32 v14, v5
	v_mul_f32_e32 v212, v212, v4
	v_pk_mul_f32 v[46:47], v[46:47], v[4:5] op_sel_hi:[1,0]
	v_pk_mul_f32 v[44:45], v[44:45], v[4:5] op_sel_hi:[1,0]
	v_pk_mul_f32 v[42:43], v[42:43], v[4:5] op_sel_hi:[1,0]
	v_pk_mul_f32 v[40:41], v[40:41], v[4:5] op_sel_hi:[1,0]
	v_pk_mul_f32 v[38:39], v[38:39], v[4:5] op_sel_hi:[1,0]
	v_pk_mul_f32 v[36:37], v[36:37], v[4:5] op_sel_hi:[1,0]
	v_pk_mul_f32 v[34:35], v[34:35], v[4:5] op_sel_hi:[1,0]
	v_pk_mul_f32 v[32:33], v[32:33], v[4:5] op_sel_hi:[1,0]
	v_pk_mul_f32 v[30:31], v[30:31], v[4:5] op_sel_hi:[1,0]
	v_pk_mul_f32 v[28:29], v[28:29], v[4:5] op_sel_hi:[1,0]
	v_pk_mul_f32 v[26:27], v[26:27], v[4:5] op_sel_hi:[1,0]
	v_pk_mul_f32 v[24:25], v[24:25], v[4:5] op_sel_hi:[1,0]
	v_pk_mul_f32 v[22:23], v[22:23], v[4:5] op_sel_hi:[1,0]
	v_pk_mul_f32 v[20:21], v[20:21], v[4:5] op_sel_hi:[1,0]
	v_pk_mul_f32 v[18:19], v[18:19], v[4:5] op_sel_hi:[1,0]
	v_pk_mul_f32 v[16:17], v[16:17], v[4:5] op_sel_hi:[1,0]
	s_branch .LBB0_647
